# c1: gla_b gate/weight loads issued before the k/v wait so both round trips overlap (counted vmcnt ladder 22..19)
# baseline (speedup 1.0000x reference)
; __device__ __forceinline__ float bf2f(bf16_t v) { return __uint_as_float(((unsigned)v) << 16); }
; __device__ __forceinline__ int ltid() { int t = threadIdx.x; asm volatile("" : "+v"(t)); return t; }
; __device__ __forceinline__ void gla_b(const Args& a, int l, int hd, int dir, int t0, unsigned char* sm, const bf16_t* __restrict__ PLR) {
;     ...
;     for (int i = tid; i < 2048; i += 512) W2s[i] = w2[(i >> 7) * 512 + (i & 127)];
;     if (tid < 128) Bs[tid] = a.in[19][(l * 2 + dir) * 512 + hd * 128 + tid];
;     for (int i = tid; i < 1024; i += 512) { const int j = i >> 4, r = i & 15; lrs[i] = bf2f(PLR[(size_t)(t0 + j) * 256 + dir * 16 + r]); }
;     __syncthreads();
; __device__ __forceinline__ void gla_load_vT(const bf16_t* __restrict__ PC, int hd, int t0, unsigned char* sm) {
;     bf16_t* vT = (bf16_t*)(sm + G_VT);
;     const int tid = ltid(), j = tid >> 3, v0 = (tid & 7) * 32;
;     const bf16_t* vp = PC + (size_t)(t0 + j) * 3072 + 1024 + hd * 256 + v0;
; #pragma unroll
;     for (int i = 0; i < 4; ++i) {
;         const u32x4 w = *(const u32x4*)(vp + i * 8);
;         const int b = v0 + i * 8;
;         vT[(b + 0) * 72 + j] = (bf16_t)(w.x & 0xffff); vT[(b + 1) * 72 + j] = (bf16_t)(w.x >> 16);
;         vT[(b + 2) * 72 + j] = (bf16_t)(w.y & 0xffff); vT[(b + 3) * 72 + j] = (bf16_t)(w.y >> 16);
;         vT[(b + 4) * 72 + j] = (bf16_t)(w.z & 0xffff); vT[(b + 5) * 72 + j] = (bf16_t)(w.z >> 16);
;         vT[(b + 6) * 72 + j] = (bf16_t)(w.w & 0xffff); vT[(b + 7) * 72 + j] = (bf16_t)(w.w >> 16);
;     }
.LBB0_223:
	s_lshl_b32 s0, s28, 6
	s_and_b32 s29, s0, 0x3fc0
	v_readlane_b32 s0, v246, 29
	v_readlane_b32 s1, v246, 30
	s_bfe_u32 s2, s28, 0x20008
	v_add_u32_e32 v0, s29, v122
	v_mov_b64_e32 v[8:9], s[0:1]
	s_movk_i32 s3, 0x1800
	v_mad_i64_i32 v[0:1], s[0:1], v0, s3, v[8:9]
	s_lshl_b32 s20, s2, 8
	v_lshl_add_u64 v[0:1], v[0:1], 0, s[20:21]
	v_lshl_add_u64 v[4:5], v[0:1], 0, v[64:65]
	v_mov_b32_e32 v10, v171
	global_load_dwordx4 v[0:3], v[4:5], off offset:1040
	s_nop 0
	global_load_dwordx4 v[4:7], v[4:5], off offset:1024
	s_lshl_b32 s20, s2, 9
	v_ashrrev_i32_e32 v28, 3, v10
	v_lshlrev_b32_e32 v10, 5, v10
	v_and_b32_e32 v29, 0xe0, v10
	v_add_u32_e32 v10, s29, v28
	v_mad_i64_i32 v[8:9], s[0:1], v10, s3, v[8:9]
	v_lshl_add_u64 v[8:9], v[8:9], 0, s[20:21]
	v_lshlrev_b32_e32 v10, 1, v29
	v_mov_b32_e32 v11, v65
	v_lshl_add_u64 v[8:9], v[8:9], 0, v[10:11]
	global_load_dwordx4 v[12:15], v[8:9], off offset:2048
	global_load_dwordx4 v[16:19], v[8:9], off offset:2064
	global_load_dwordx4 v[20:23], v[8:9], off offset:2080
	global_load_dwordx4 v[24:27], v[8:9], off offset:2096
	s_ashr_i32 s20, s28, 10
	v_readlane_b32 s0, v246, 35
	v_mul_u32_u24_e32 v9, 0x48, v29
	s_add_i32 s4, s20, s0
	v_lshlrev_b32_e32 v8, 1, v28
	v_lshlrev_b32_e32 v9, 1, v9
	v_readlane_b32 s0, v248, 20
	v_mov_b32_e32 v10, v171
	s_lshl_b32 s38, s2, 7
	v_add3_u32 v11, s0, v8, v9
	v_add3_u32 v8, s0, v9, v8
	s_movk_i32 s0, 0x800
	v_readlane_b32 s30, v247, 1
	v_readlane_b32 s31, v247, 2
	v_readlane_b32 s36, v247, 3
	v_readlane_b32 s37, v247, 4
	v_readlane_b32 s0, v246, 13
	v_readlane_b32 s1, v246, 14
	s_nop 3
	s_lshl_b32 s2, s4, 15
	s_add_u32 s30, s30, s2
	s_addc_u32 s31, s31, 0
	s_lshl_b32 s2, s38, 2
	s_add_u32 s30, s30, s2
	s_addc_u32 s31, s31, 0
	s_lshl_b32 s2, s4, 9
	s_or_b32 s2, s2, s38
	s_lshl_b32 s2, s2, 2
	s_add_u32 s36, s36, s2
	s_addc_u32 s37, s37, 0
	s_lshl_b32 s2, s20, 5
	s_add_u32 s0, s0, s2
	s_addc_u32 s1, s1, 0
	s_lshl_b32 s2, s29, 9
	s_add_u32 s0, s0, s2
	s_addc_u32 s1, s1, 0
	v_and_b32_e32 v134, 0x7f, v171
	v_lshlrev_b32_e32 v134, 2, v134
	v_lshlrev_b32_e32 v135, 2, v171
	v_lshrrev_b32_e32 v136, 4, v171
	v_lshlrev_b32_e32 v136, 9, v136
	v_and_b32_e32 v137, 15, v171
	v_lshl_or_b32 v136, v137, 1, v136
	v_add_u32_e32 v137, 0x4000, v136
	global_load_ushort v138, v136, s[0:1]
	global_load_ushort v139, v137, s[0:1]
	global_load_dword v140, v134, s[36:37]
	global_load_dword v201, v134, s[30:31]
	global_load_dword v202, v134, s[30:31] offset:2048
	s_add_u32 s30, s30, 0x1000
	s_addc_u32 s31, s31, 0
	global_load_dword v203, v134, s[30:31]
	global_load_dword v204, v134, s[30:31] offset:2048
	s_add_u32 s30, s30, 0x1000
	s_addc_u32 s31, s31, 0
	global_load_dword v205, v134, s[30:31]
	global_load_dword v206, v134, s[30:31] offset:2048
	s_add_u32 s30, s30, 0x1000
	s_addc_u32 s31, s31, 0
	global_load_dword v207, v134, s[30:31]
	global_load_dword v208, v134, s[30:31] offset:2048
	s_add_u32 s30, s30, 0x1000
	s_addc_u32 s31, s31, 0
	global_load_dword v209, v134, s[30:31]
	global_load_dword v210, v134, s[30:31] offset:2048
	s_add_u32 s30, s30, 0x1000
	s_addc_u32 s31, s31, 0
	global_load_dword v211, v134, s[30:31]
	global_load_dword v212, v134, s[30:31] offset:2048
	s_add_u32 s30, s30, 0x1000
	s_addc_u32 s31, s31, 0
	global_load_dword v213, v134, s[30:31]
	global_load_dword v214, v134, s[30:31] offset:2048
	s_add_u32 s30, s30, 0x1000
	s_addc_u32 s31, s31, 0
	global_load_dword v215, v134, s[30:31]
	global_load_dword v216, v134, s[30:31] offset:2048
	s_waitcnt vmcnt(22)
	ds_write_b16 v11, v12
	ds_write_b16_d16_hi v8, v12 offset:144
	ds_write_b16 v8, v13 offset:288
	ds_write_b16_d16_hi v8, v13 offset:432
	ds_write_b16 v8, v14 offset:576
	ds_write_b16_d16_hi v8, v14 offset:720
	ds_write_b16 v8, v15 offset:864
	ds_write_b16_d16_hi v8, v15 offset:1008
	s_waitcnt vmcnt(21)
	ds_write_b16 v11, v16 offset:1152
	ds_write_b16_d16_hi v8, v16 offset:1296
	ds_write_b16 v8, v17 offset:1440
	ds_write_b16_d16_hi v8, v17 offset:1584
	ds_write_b16 v8, v18 offset:1728
	ds_write_b16_d16_hi v8, v18 offset:1872
	ds_write_b16 v8, v19 offset:2016
	ds_write_b16_d16_hi v8, v19 offset:2160
	s_waitcnt vmcnt(20)
	ds_write_b16 v11, v20 offset:2304
	ds_write_b16_d16_hi v8, v20 offset:2448
	ds_write_b16 v8, v21 offset:2592
	ds_write_b16_d16_hi v8, v21 offset:2736
	ds_write_b16 v8, v22 offset:2880
	ds_write_b16_d16_hi v8, v22 offset:3024
	ds_write_b16 v8, v23 offset:3168
	ds_write_b16_d16_hi v8, v23 offset:3312
	s_waitcnt vmcnt(19)
	ds_write_b16 v11, v24 offset:3456
	ds_write_b16_d16_hi v8, v24 offset:3600
	ds_write_b16 v8, v25 offset:3744
	ds_write_b16_d16_hi v8, v25 offset:3888
	ds_write_b16 v8, v26 offset:4032
	ds_write_b16_d16_hi v8, v26 offset:4176
	ds_write_b16 v8, v27 offset:4320
	ds_write_b16_d16_hi v8, v27 offset:4464
	s_waitcnt vmcnt(17)
	v_lshlrev_b32_e32 v138, 16, v138
	v_lshlrev_b32_e32 v139, 16, v139
	ds_write_b32 v135, v138 offset:41728
	ds_write_b32 v135, v139 offset:43776
	s_waitcnt lgkmcnt(0)
	s_barrier
; __device__ __forceinline__ void gla_b(const Args& a, int l, int hd, int dir, int t0, unsigned char* sm, const bf16_t* __restrict__ PLR) {
;     ...
;     const int d = tid & 127, q = tid >> 7;
;     float run = 0.f;
;     for (int k = 0; k < 16; ++k) {
;         const int s = q * 16 + k, j = dir ? 63 - s : s;
;         float x = Bs[d];
; #pragma unroll
;         for (int r = 0; r < 16; ++r) x += lrs[j * 16 + r] * W2s[r * 128 + d];
;         const float g = (fminf(x, 0.f) - __logf(1.f + __expf(-fabsf(x)))) * (1.f / 16.f);
;         run += g; Gb[j * 129 + d] = run;
;     }
	v_lshrrev_b32_e32 v15, 7, v171
	v_lshlrev_b32_e32 v15, 4, v15
	v_sub_u32_e32 v16, 63, v15
	s_cmpk_lt_u32 s28, 0x400
	s_cselect_b64 s[0:1], -1, 0
	s_cselect_b32 s3, 64, 0xffffffc0
	s_movk_i32 s101, 0x204
	s_cselect_b32 s101, s101, 0xfffffdfc
	v_cndmask_b32_e64 v15, v16, v15, s[0:1]
	v_lshlrev_b32_e32 v27, 6, v15
	v_add_u32_e32 v27, 0xa300, v27
	v_add_u32_e32 v28, s3, v27
	v_mul_u32_u24_e32 v16, 0x204, v15
	v_add_u32_e32 v16, v16, v134
	s_lshl_b32 s100, s3, 1
	ds_read_b128 v[172:175], v27
	ds_read_b128 v[176:179], v27 offset:16
	ds_read_b128 v[180:183], v27 offset:32
	ds_read_b128 v[164:167], v27 offset:48
	ds_read_b128 v[228:231], v28
	ds_read_b128 v[232:235], v28 offset:16
	ds_read_b128 v[236:239], v28 offset:32
	ds_read_b128 v[240:243], v28 offset:48
	s_mov_b32 s2, 0x3d800000
	s_waitcnt vmcnt(0)
	s_waitcnt lgkmcnt(0)
	v_mov_b32_e32 v25, v140
	v_mov_b32_e32 v26, v140
	v_fmac_f32_e32 v25, v172, v201
	v_fmac_f32_e32 v26, v228, v201
	v_fmac_f32_e32 v25, v173, v202
	v_fmac_f32_e32 v26, v229, v202
	v_fmac_f32_e32 v25, v174, v203
	v_fmac_f32_e32 v26, v230, v203
	v_fmac_f32_e32 v25, v175, v204
	v_fmac_f32_e32 v26, v231, v204
	v_fmac_f32_e32 v25, v176, v205
	v_fmac_f32_e32 v26, v232, v205
	v_fmac_f32_e32 v25, v177, v206
	v_fmac_f32_e32 v26, v233, v206
	v_fmac_f32_e32 v25, v178, v207
	v_fmac_f32_e32 v26, v234, v207
	v_fmac_f32_e32 v25, v179, v208
	v_fmac_f32_e32 v26, v235, v208
	v_fmac_f32_e32 v25, v180, v209
	v_fmac_f32_e32 v26, v236, v209
	v_fmac_f32_e32 v25, v181, v210
	v_fmac_f32_e32 v26, v237, v210
	v_fmac_f32_e32 v25, v182, v211
	v_fmac_f32_e32 v26, v238, v211
	v_fmac_f32_e32 v25, v183, v212
	v_fmac_f32_e32 v26, v239, v212
	v_fmac_f32_e32 v25, v164, v213
	v_fmac_f32_e32 v26, v240, v213
	v_fmac_f32_e32 v25, v165, v214
	v_fmac_f32_e32 v26, v241, v214
	v_fmac_f32_e32 v25, v166, v215
	v_fmac_f32_e32 v26, v242, v215
	v_fmac_f32_e32 v25, v167, v216
	v_fmac_f32_e32 v26, v243, v216
	v_add_u32_e32 v27, s100, v27
	v_add_u32_e32 v28, s100, v28
	ds_read_b128 v[172:175], v27
	ds_read_b128 v[176:179], v27 offset:16
	ds_read_b128 v[180:183], v27 offset:32
	ds_read_b128 v[164:167], v27 offset:48
	ds_read_b128 v[228:231], v28
	ds_read_b128 v[232:235], v28 offset:16
	ds_read_b128 v[236:239], v28 offset:32
	ds_read_b128 v[240:243], v28 offset:48
	v_mul_f32_e64 v17, |v25|, s61
	v_mul_f32_e64 v18, |v26|, s61
	v_exp_f32_e32 v17, v17
	v_exp_f32_e32 v18, v18
	v_min_f32_e32 v19, 0, v25
	v_min_f32_e32 v20, 0, v26
	v_add_f32_e32 v17, 1.0, v17
	v_add_f32_e32 v18, 1.0, v18
	v_cmp_gt_f32_e64 s[4:5], s24, v17
	v_cmp_gt_f32_e64 s[6:7], s24, v18
	s_nop 1
	v_cndmask_b32_e64 v21, 0, 32, s[4:5]
	v_cndmask_b32_e64 v22, 0, 32, s[6:7]
	v_ldexp_f32 v17, v17, v21
	v_ldexp_f32 v18, v18, v22
	v_log_f32_e32 v17, v17
	v_log_f32_e32 v18, v18
	v_cndmask_b32_e64 v21, 0, v192, s[4:5]
	v_cndmask_b32_e64 v22, 0, v192, s[6:7]
	v_mul_f32_e32 v23, 0x3f317217, v17
	v_mul_f32_e32 v24, 0x3f317217, v18
	v_fma_f32 v23, v17, s62, -v23
	v_fma_f32 v24, v18, s62, -v24
	v_fmac_f32_e32 v23, 0x3377d1cf, v17
	v_fmac_f32_e32 v24, 0x3377d1cf, v18
	v_fmac_f32_e32 v23, 0x3f317217, v17
	v_fmac_f32_e32 v24, 0x3f317217, v18
	v_cmp_lt_f32_e64 s[30:31], |v17|, s63
	v_cmp_lt_f32_e64 s[36:37], |v18|, s63
	s_nop 1
	v_cndmask_b32_e64 v17, v17, v23, s[30:31]
	v_cndmask_b32_e64 v18, v18, v24, s[36:37]
	v_sub_f32_e32 v17, v17, v21
	v_sub_f32_e32 v18, v18, v22
	v_sub_f32_e32 v17, v19, v17
	v_sub_f32_e32 v18, v20, v18
	v_fma_f32 v217, v17, s2, v65
	v_fma_f32 v218, v18, s2, v217
	s_waitcnt lgkmcnt(0)
	v_mov_b32_e32 v25, v140
	v_mov_b32_e32 v26, v140
	v_fmac_f32_e32 v25, v172, v201
	v_fmac_f32_e32 v26, v228, v201
	v_fmac_f32_e32 v25, v173, v202
	v_fmac_f32_e32 v26, v229, v202
	v_fmac_f32_e32 v25, v174, v203
	v_fmac_f32_e32 v26, v230, v203
	v_fmac_f32_e32 v25, v175, v204
	v_fmac_f32_e32 v26, v231, v204
	v_fmac_f32_e32 v25, v176, v205
	v_fmac_f32_e32 v26, v232, v205
	v_fmac_f32_e32 v25, v177, v206
	v_fmac_f32_e32 v26, v233, v206
	v_fmac_f32_e32 v25, v178, v207
	v_fmac_f32_e32 v26, v234, v207
	v_fmac_f32_e32 v25, v179, v208
	v_fmac_f32_e32 v26, v235, v208
	v_fmac_f32_e32 v25, v180, v209
	v_fmac_f32_e32 v26, v236, v209
	v_fmac_f32_e32 v25, v181, v210
	v_fmac_f32_e32 v26, v237, v210
	v_fmac_f32_e32 v25, v182, v211
	v_fmac_f32_e32 v26, v238, v211
	v_fmac_f32_e32 v25, v183, v212
	v_fmac_f32_e32 v26, v239, v212
	v_fmac_f32_e32 v25, v164, v213
	v_fmac_f32_e32 v26, v240, v213
	v_fmac_f32_e32 v25, v165, v214
	v_fmac_f32_e32 v26, v241, v214
	v_fmac_f32_e32 v25, v166, v215
	v_fmac_f32_e32 v26, v242, v215
	v_fmac_f32_e32 v25, v167, v216
	v_fmac_f32_e32 v26, v243, v216
	v_add_u32_e32 v27, s100, v27
	v_add_u32_e32 v28, s100, v28
	ds_read_b128 v[172:175], v27
	ds_read_b128 v[176:179], v27 offset:16
	ds_read_b128 v[180:183], v27 offset:32
	ds_read_b128 v[164:167], v27 offset:48
	ds_read_b128 v[228:231], v28
	ds_read_b128 v[232:235], v28 offset:16
	ds_read_b128 v[236:239], v28 offset:32
	ds_read_b128 v[240:243], v28 offset:48
	v_mul_f32_e64 v17, |v25|, s61
	v_mul_f32_e64 v18, |v26|, s61
	v_exp_f32_e32 v17, v17
	v_exp_f32_e32 v18, v18
	v_min_f32_e32 v19, 0, v25
	v_min_f32_e32 v20, 0, v26
	v_add_f32_e32 v17, 1.0, v17
	v_add_f32_e32 v18, 1.0, v18
	v_cmp_gt_f32_e64 s[4:5], s24, v17
	v_cmp_gt_f32_e64 s[6:7], s24, v18
	s_nop 1
	v_cndmask_b32_e64 v21, 0, 32, s[4:5]
	v_cndmask_b32_e64 v22, 0, 32, s[6:7]
	v_ldexp_f32 v17, v17, v21
	v_ldexp_f32 v18, v18, v22
	v_log_f32_e32 v17, v17
	v_log_f32_e32 v18, v18
	v_cndmask_b32_e64 v21, 0, v192, s[4:5]
	v_cndmask_b32_e64 v22, 0, v192, s[6:7]
	v_mul_f32_e32 v23, 0x3f317217, v17
	v_mul_f32_e32 v24, 0x3f317217, v18
	v_fma_f32 v23, v17, s62, -v23
	v_fma_f32 v24, v18, s62, -v24
	v_fmac_f32_e32 v23, 0x3377d1cf, v17
	v_fmac_f32_e32 v24, 0x3377d1cf, v18
	v_fmac_f32_e32 v23, 0x3f317217, v17
	v_fmac_f32_e32 v24, 0x3f317217, v18
	v_cmp_lt_f32_e64 s[30:31], |v17|, s63
	v_cmp_lt_f32_e64 s[36:37], |v18|, s63
	s_nop 1
	v_cndmask_b32_e64 v17, v17, v23, s[30:31]
	v_cndmask_b32_e64 v18, v18, v24, s[36:37]
	v_sub_f32_e32 v17, v17, v21
	v_sub_f32_e32 v18, v18, v22
	v_sub_f32_e32 v17, v19, v17
	v_sub_f32_e32 v18, v20, v18
	v_fma_f32 v219, v17, s2, v218
	v_fma_f32 v220, v18, s2, v219
	s_waitcnt lgkmcnt(0)
; __device__ __forceinline__ void gla_b(const Args& a, int l, int hd, int dir, int t0, unsigned char* sm, const bf16_t* __restrict__ PLR) {
;     ...
;     for (int k = 0; k < 16; ++k) {
;         const int s = q * 16 + k, j = dir ? 63 - s : s;
;         float x = Bs[d];
; #pragma unroll
;         for (int r = 0; r < 16; ++r) x += lrs[j * 16 + r] * W2s[r * 128 + d];
;         const float g = (fminf(x, 0.f) - __logf(1.f + __expf(-fabsf(x)))) * (1.f / 16.f);
;         run += g; Gb[j * 129 + d] = run;
;     }
	v_mov_b32_e32 v25, v140
	v_mov_b32_e32 v26, v140
	v_fmac_f32_e32 v25, v172, v201
	v_fmac_f32_e32 v26, v228, v201
	v_fmac_f32_e32 v25, v173, v202
	v_fmac_f32_e32 v26, v229, v202
	v_fmac_f32_e32 v25, v174, v203
	v_fmac_f32_e32 v26, v230, v203
	v_fmac_f32_e32 v25, v175, v204
	v_fmac_f32_e32 v26, v231, v204
	v_fmac_f32_e32 v25, v176, v205
	v_fmac_f32_e32 v26, v232, v205
	v_fmac_f32_e32 v25, v177, v206
	v_fmac_f32_e32 v26, v233, v206
	v_fmac_f32_e32 v25, v178, v207
	v_fmac_f32_e32 v26, v234, v207
	v_fmac_f32_e32 v25, v179, v208
	v_fmac_f32_e32 v26, v235, v208
	v_fmac_f32_e32 v25, v180, v209
	v_fmac_f32_e32 v26, v236, v209
	v_fmac_f32_e32 v25, v181, v210
	v_fmac_f32_e32 v26, v237, v210
	v_fmac_f32_e32 v25, v182, v211
	v_fmac_f32_e32 v26, v238, v211
	v_fmac_f32_e32 v25, v183, v212
	v_fmac_f32_e32 v26, v239, v212
	v_fmac_f32_e32 v25, v164, v213
	v_fmac_f32_e32 v26, v240, v213
	v_fmac_f32_e32 v25, v165, v214
	v_fmac_f32_e32 v26, v241, v214
	v_fmac_f32_e32 v25, v166, v215
	v_fmac_f32_e32 v26, v242, v215
	v_fmac_f32_e32 v25, v167, v216
	v_fmac_f32_e32 v26, v243, v216
	v_add_u32_e32 v27, s100, v27
	v_add_u32_e32 v28, s100, v28
	ds_read_b128 v[172:175], v27
	ds_read_b128 v[176:179], v27 offset:16
	ds_read_b128 v[180:183], v27 offset:32
	ds_read_b128 v[164:167], v27 offset:48
	ds_read_b128 v[228:231], v28
	ds_read_b128 v[232:235], v28 offset:16
	ds_read_b128 v[236:239], v28 offset:32
	ds_read_b128 v[240:243], v28 offset:48
	v_mul_f32_e64 v17, |v25|, s61
	v_mul_f32_e64 v18, |v26|, s61
	v_exp_f32_e32 v17, v17
	v_exp_f32_e32 v18, v18
	v_min_f32_e32 v19, 0, v25
	v_min_f32_e32 v20, 0, v26
	v_add_f32_e32 v17, 1.0, v17
	v_add_f32_e32 v18, 1.0, v18
	v_cmp_gt_f32_e64 s[4:5], s24, v17
	v_cmp_gt_f32_e64 s[6:7], s24, v18
	s_nop 1
	v_cndmask_b32_e64 v21, 0, 32, s[4:5]
	v_cndmask_b32_e64 v22, 0, 32, s[6:7]
	v_ldexp_f32 v17, v17, v21
	v_ldexp_f32 v18, v18, v22
	v_log_f32_e32 v17, v17
	v_log_f32_e32 v18, v18
	v_cndmask_b32_e64 v21, 0, v192, s[4:5]
	v_cndmask_b32_e64 v22, 0, v192, s[6:7]
	v_mul_f32_e32 v23, 0x3f317217, v17
	v_mul_f32_e32 v24, 0x3f317217, v18
	v_fma_f32 v23, v17, s62, -v23
	v_fma_f32 v24, v18, s62, -v24
	v_fmac_f32_e32 v23, 0x3377d1cf, v17
	v_fmac_f32_e32 v24, 0x3377d1cf, v18
	v_fmac_f32_e32 v23, 0x3f317217, v17
	v_fmac_f32_e32 v24, 0x3f317217, v18
	v_cmp_lt_f32_e64 s[30:31], |v17|, s63
	v_cmp_lt_f32_e64 s[36:37], |v18|, s63
	s_nop 1
	v_cndmask_b32_e64 v17, v17, v23, s[30:31]
	v_cndmask_b32_e64 v18, v18, v24, s[36:37]
	v_sub_f32_e32 v17, v17, v21
	v_sub_f32_e32 v18, v18, v22
	v_sub_f32_e32 v17, v19, v17
	v_sub_f32_e32 v18, v20, v18
	v_fma_f32 v221, v17, s2, v220
	v_fma_f32 v222, v18, s2, v221
	s_waitcnt lgkmcnt(0)
	v_mov_b32_e32 v25, v140
	v_mov_b32_e32 v26, v140
	v_fmac_f32_e32 v25, v172, v201
	v_fmac_f32_e32 v26, v228, v201
	v_fmac_f32_e32 v25, v173, v202
	v_fmac_f32_e32 v26, v229, v202
	v_fmac_f32_e32 v25, v174, v203
	v_fmac_f32_e32 v26, v230, v203
	v_fmac_f32_e32 v25, v175, v204
	v_fmac_f32_e32 v26, v231, v204
	v_fmac_f32_e32 v25, v176, v205
	v_fmac_f32_e32 v26, v232, v205
	v_fmac_f32_e32 v25, v177, v206
	v_fmac_f32_e32 v26, v233, v206
	v_fmac_f32_e32 v25, v178, v207
	v_fmac_f32_e32 v26, v234, v207
	v_fmac_f32_e32 v25, v179, v208
	v_fmac_f32_e32 v26, v235, v208
	v_fmac_f32_e32 v25, v180, v209
	v_fmac_f32_e32 v26, v236, v209
	v_fmac_f32_e32 v25, v181, v210
	v_fmac_f32_e32 v26, v237, v210
	v_fmac_f32_e32 v25, v182, v211
	v_fmac_f32_e32 v26, v238, v211
	v_fmac_f32_e32 v25, v183, v212
	v_fmac_f32_e32 v26, v239, v212
	v_fmac_f32_e32 v25, v164, v213
	v_fmac_f32_e32 v26, v240, v213
	v_fmac_f32_e32 v25, v165, v214
	v_fmac_f32_e32 v26, v241, v214
	v_fmac_f32_e32 v25, v166, v215
	v_fmac_f32_e32 v26, v242, v215
	v_fmac_f32_e32 v25, v167, v216
	v_fmac_f32_e32 v26, v243, v216
	v_add_u32_e32 v27, s100, v27
	v_add_u32_e32 v28, s100, v28
	ds_read_b128 v[172:175], v27
	ds_read_b128 v[176:179], v27 offset:16
	ds_read_b128 v[180:183], v27 offset:32
	ds_read_b128 v[164:167], v27 offset:48
	ds_read_b128 v[228:231], v28
	ds_read_b128 v[232:235], v28 offset:16
	ds_read_b128 v[236:239], v28 offset:32
	ds_read_b128 v[240:243], v28 offset:48
	v_mul_f32_e64 v17, |v25|, s61
	v_mul_f32_e64 v18, |v26|, s61
	v_exp_f32_e32 v17, v17
	v_exp_f32_e32 v18, v18
	v_min_f32_e32 v19, 0, v25
	v_min_f32_e32 v20, 0, v26
	v_add_f32_e32 v17, 1.0, v17
	v_add_f32_e32 v18, 1.0, v18
	v_cmp_gt_f32_e64 s[4:5], s24, v17
	v_cmp_gt_f32_e64 s[6:7], s24, v18
	s_nop 1
	v_cndmask_b32_e64 v21, 0, 32, s[4:5]
	v_cndmask_b32_e64 v22, 0, 32, s[6:7]
	v_ldexp_f32 v17, v17, v21
	v_ldexp_f32 v18, v18, v22
	v_log_f32_e32 v17, v17
	v_log_f32_e32 v18, v18
	v_cndmask_b32_e64 v21, 0, v192, s[4:5]
	v_cndmask_b32_e64 v22, 0, v192, s[6:7]
	v_mul_f32_e32 v23, 0x3f317217, v17
	v_mul_f32_e32 v24, 0x3f317217, v18
	v_fma_f32 v23, v17, s62, -v23
	v_fma_f32 v24, v18, s62, -v24
	v_fmac_f32_e32 v23, 0x3377d1cf, v17
	v_fmac_f32_e32 v24, 0x3377d1cf, v18
	v_fmac_f32_e32 v23, 0x3f317217, v17
	v_fmac_f32_e32 v24, 0x3f317217, v18
	v_cmp_lt_f32_e64 s[30:31], |v17|, s63
	v_cmp_lt_f32_e64 s[36:37], |v18|, s63
	s_nop 1
	v_cndmask_b32_e64 v17, v17, v23, s[30:31]
	v_cndmask_b32_e64 v18, v18, v24, s[36:37]
	v_sub_f32_e32 v17, v17, v21
	v_sub_f32_e32 v18, v18, v22
	v_sub_f32_e32 v17, v19, v17
	v_sub_f32_e32 v18, v20, v18
	v_fma_f32 v223, v17, s2, v222
	v_fma_f32 v224, v18, s2, v223
	s_waitcnt lgkmcnt(0)
; __device__ __forceinline__ void gla_b(const Args& a, int l, int hd, int dir, int t0, unsigned char* sm, const bf16_t* __restrict__ PLR) {
;     ...
;     for (int k = 0; k < 16; ++k) {
;         const int s = q * 16 + k, j = dir ? 63 - s : s;
;         float x = Bs[d];
; #pragma unroll
;         for (int r = 0; r < 16; ++r) x += lrs[j * 16 + r] * W2s[r * 128 + d];
;         const float g = (fminf(x, 0.f) - __logf(1.f + __expf(-fabsf(x)))) * (1.f / 16.f);
;         run += g; Gb[j * 129 + d] = run;
;     }
	v_mov_b32_e32 v25, v140
	v_mov_b32_e32 v26, v140
	v_fmac_f32_e32 v25, v172, v201
	v_fmac_f32_e32 v26, v228, v201
	v_fmac_f32_e32 v25, v173, v202
	v_fmac_f32_e32 v26, v229, v202
	v_fmac_f32_e32 v25, v174, v203
	v_fmac_f32_e32 v26, v230, v203
	v_fmac_f32_e32 v25, v175, v204
	v_fmac_f32_e32 v26, v231, v204
	v_fmac_f32_e32 v25, v176, v205
	v_fmac_f32_e32 v26, v232, v205
	v_fmac_f32_e32 v25, v177, v206
	v_fmac_f32_e32 v26, v233, v206
	v_fmac_f32_e32 v25, v178, v207
	v_fmac_f32_e32 v26, v234, v207
	v_fmac_f32_e32 v25, v179, v208
	v_fmac_f32_e32 v26, v235, v208
	v_fmac_f32_e32 v25, v180, v209
	v_fmac_f32_e32 v26, v236, v209
	v_fmac_f32_e32 v25, v181, v210
	v_fmac_f32_e32 v26, v237, v210
	v_fmac_f32_e32 v25, v182, v211
	v_fmac_f32_e32 v26, v238, v211
	v_fmac_f32_e32 v25, v183, v212
	v_fmac_f32_e32 v26, v239, v212
	v_fmac_f32_e32 v25, v164, v213
	v_fmac_f32_e32 v26, v240, v213
	v_fmac_f32_e32 v25, v165, v214
	v_fmac_f32_e32 v26, v241, v214
	v_fmac_f32_e32 v25, v166, v215
	v_fmac_f32_e32 v26, v242, v215
	v_fmac_f32_e32 v25, v167, v216
	v_fmac_f32_e32 v26, v243, v216
	v_add_u32_e32 v27, s100, v27
	v_add_u32_e32 v28, s100, v28
	ds_read_b128 v[172:175], v27
	ds_read_b128 v[176:179], v27 offset:16
	ds_read_b128 v[180:183], v27 offset:32
	ds_read_b128 v[164:167], v27 offset:48
	ds_read_b128 v[228:231], v28
	ds_read_b128 v[232:235], v28 offset:16
	ds_read_b128 v[236:239], v28 offset:32
	ds_read_b128 v[240:243], v28 offset:48
	v_mul_f32_e64 v17, |v25|, s61
	v_mul_f32_e64 v18, |v26|, s61
	v_exp_f32_e32 v17, v17
	v_exp_f32_e32 v18, v18
	v_min_f32_e32 v19, 0, v25
	v_min_f32_e32 v20, 0, v26
	v_add_f32_e32 v17, 1.0, v17
	v_add_f32_e32 v18, 1.0, v18
	v_cmp_gt_f32_e64 s[4:5], s24, v17
	v_cmp_gt_f32_e64 s[6:7], s24, v18
	s_nop 1
	v_cndmask_b32_e64 v21, 0, 32, s[4:5]
	v_cndmask_b32_e64 v22, 0, 32, s[6:7]
	v_ldexp_f32 v17, v17, v21
	v_ldexp_f32 v18, v18, v22
	v_log_f32_e32 v17, v17
	v_log_f32_e32 v18, v18
	v_cndmask_b32_e64 v21, 0, v192, s[4:5]
	v_cndmask_b32_e64 v22, 0, v192, s[6:7]
	v_mul_f32_e32 v23, 0x3f317217, v17
	v_mul_f32_e32 v24, 0x3f317217, v18
	v_fma_f32 v23, v17, s62, -v23
	v_fma_f32 v24, v18, s62, -v24
	v_fmac_f32_e32 v23, 0x3377d1cf, v17
	v_fmac_f32_e32 v24, 0x3377d1cf, v18
	v_fmac_f32_e32 v23, 0x3f317217, v17
	v_fmac_f32_e32 v24, 0x3f317217, v18
	v_cmp_lt_f32_e64 s[30:31], |v17|, s63
	v_cmp_lt_f32_e64 s[36:37], |v18|, s63
	s_nop 1
	v_cndmask_b32_e64 v17, v17, v23, s[30:31]
	v_cndmask_b32_e64 v18, v18, v24, s[36:37]
	v_sub_f32_e32 v17, v17, v21
	v_sub_f32_e32 v18, v18, v22
	v_sub_f32_e32 v17, v19, v17
	v_sub_f32_e32 v18, v20, v18
	v_fma_f32 v225, v17, s2, v224
	v_fma_f32 v226, v18, s2, v225
	s_waitcnt lgkmcnt(0)
	v_mov_b32_e32 v25, v140
	v_mov_b32_e32 v26, v140
	v_fmac_f32_e32 v25, v172, v201
	v_fmac_f32_e32 v26, v228, v201
	v_fmac_f32_e32 v25, v173, v202
	v_fmac_f32_e32 v26, v229, v202
	v_fmac_f32_e32 v25, v174, v203
	v_fmac_f32_e32 v26, v230, v203
	v_fmac_f32_e32 v25, v175, v204
	v_fmac_f32_e32 v26, v231, v204
	v_fmac_f32_e32 v25, v176, v205
	v_fmac_f32_e32 v26, v232, v205
	v_fmac_f32_e32 v25, v177, v206
	v_fmac_f32_e32 v26, v233, v206
	v_fmac_f32_e32 v25, v178, v207
	v_fmac_f32_e32 v26, v234, v207
	v_fmac_f32_e32 v25, v179, v208
	v_fmac_f32_e32 v26, v235, v208
	v_fmac_f32_e32 v25, v180, v209
	v_fmac_f32_e32 v26, v236, v209
	v_fmac_f32_e32 v25, v181, v210
	v_fmac_f32_e32 v26, v237, v210
	v_fmac_f32_e32 v25, v182, v211
	v_fmac_f32_e32 v26, v238, v211
	v_fmac_f32_e32 v25, v183, v212
	v_fmac_f32_e32 v26, v239, v212
	v_fmac_f32_e32 v25, v164, v213
	v_fmac_f32_e32 v26, v240, v213
	v_fmac_f32_e32 v25, v165, v214
	v_fmac_f32_e32 v26, v241, v214
	v_fmac_f32_e32 v25, v166, v215
	v_fmac_f32_e32 v26, v242, v215
	v_fmac_f32_e32 v25, v167, v216
	v_fmac_f32_e32 v26, v243, v216
	v_add_u32_e32 v27, s100, v27
	v_add_u32_e32 v28, s100, v28
	ds_read_b128 v[172:175], v27
	ds_read_b128 v[176:179], v27 offset:16
	ds_read_b128 v[180:183], v27 offset:32
	ds_read_b128 v[164:167], v27 offset:48
	ds_read_b128 v[228:231], v28
	ds_read_b128 v[232:235], v28 offset:16
	ds_read_b128 v[236:239], v28 offset:32
	ds_read_b128 v[240:243], v28 offset:48
	v_mul_f32_e64 v17, |v25|, s61
	v_mul_f32_e64 v18, |v26|, s61
	v_exp_f32_e32 v17, v17
	v_exp_f32_e32 v18, v18
	v_min_f32_e32 v19, 0, v25
	v_min_f32_e32 v20, 0, v26
	v_add_f32_e32 v17, 1.0, v17
	v_add_f32_e32 v18, 1.0, v18
	v_cmp_gt_f32_e64 s[4:5], s24, v17
	v_cmp_gt_f32_e64 s[6:7], s24, v18
	s_nop 1
	v_cndmask_b32_e64 v21, 0, 32, s[4:5]
	v_cndmask_b32_e64 v22, 0, 32, s[6:7]
	v_ldexp_f32 v17, v17, v21
	v_ldexp_f32 v18, v18, v22
	v_log_f32_e32 v17, v17
	v_log_f32_e32 v18, v18
	v_cndmask_b32_e64 v21, 0, v192, s[4:5]
	v_cndmask_b32_e64 v22, 0, v192, s[6:7]
	v_mul_f32_e32 v23, 0x3f317217, v17
	v_mul_f32_e32 v24, 0x3f317217, v18
	v_fma_f32 v23, v17, s62, -v23
	v_fma_f32 v24, v18, s62, -v24
	v_fmac_f32_e32 v23, 0x3377d1cf, v17
	v_fmac_f32_e32 v24, 0x3377d1cf, v18
	v_fmac_f32_e32 v23, 0x3f317217, v17
	v_fmac_f32_e32 v24, 0x3f317217, v18
	v_cmp_lt_f32_e64 s[30:31], |v17|, s63
	v_cmp_lt_f32_e64 s[36:37], |v18|, s63
	s_nop 1
	v_cndmask_b32_e64 v17, v17, v23, s[30:31]
	v_cndmask_b32_e64 v18, v18, v24, s[36:37]
	v_sub_f32_e32 v17, v17, v21
	v_sub_f32_e32 v18, v18, v22
	v_sub_f32_e32 v17, v19, v17
	v_sub_f32_e32 v18, v20, v18
	v_fma_f32 v227, v17, s2, v226
	v_fma_f32 v184, v18, s2, v227
	s_waitcnt lgkmcnt(0)
; __device__ __forceinline__ void gla_b(const Args& a, int l, int hd, int dir, int t0, unsigned char* sm, const bf16_t* __restrict__ PLR) {
;     ...
;     for (int k = 0; k < 16; ++k) {
;         const int s = q * 16 + k, j = dir ? 63 - s : s;
;         float x = Bs[d];
; #pragma unroll
;         for (int r = 0; r < 16; ++r) x += lrs[j * 16 + r] * W2s[r * 128 + d];
;         const float g = (fminf(x, 0.f) - __logf(1.f + __expf(-fabsf(x)))) * (1.f / 16.f);
;         run += g; Gb[j * 129 + d] = run;
;     }
;     tot[q * 128 + d] = run;
;     __syncthreads();
	v_mov_b32_e32 v25, v140
	v_mov_b32_e32 v26, v140
	v_fmac_f32_e32 v25, v172, v201
	v_fmac_f32_e32 v26, v228, v201
	v_fmac_f32_e32 v25, v173, v202
	v_fmac_f32_e32 v26, v229, v202
	v_fmac_f32_e32 v25, v174, v203
	v_fmac_f32_e32 v26, v230, v203
	v_fmac_f32_e32 v25, v175, v204
	v_fmac_f32_e32 v26, v231, v204
	v_fmac_f32_e32 v25, v176, v205
	v_fmac_f32_e32 v26, v232, v205
	v_fmac_f32_e32 v25, v177, v206
	v_fmac_f32_e32 v26, v233, v206
	v_fmac_f32_e32 v25, v178, v207
	v_fmac_f32_e32 v26, v234, v207
	v_fmac_f32_e32 v25, v179, v208
	v_fmac_f32_e32 v26, v235, v208
	v_fmac_f32_e32 v25, v180, v209
	v_fmac_f32_e32 v26, v236, v209
	v_fmac_f32_e32 v25, v181, v210
	v_fmac_f32_e32 v26, v237, v210
	v_fmac_f32_e32 v25, v182, v211
	v_fmac_f32_e32 v26, v238, v211
	v_fmac_f32_e32 v25, v183, v212
	v_fmac_f32_e32 v26, v239, v212
	v_fmac_f32_e32 v25, v164, v213
	v_fmac_f32_e32 v26, v240, v213
	v_fmac_f32_e32 v25, v165, v214
	v_fmac_f32_e32 v26, v241, v214
	v_fmac_f32_e32 v25, v166, v215
	v_fmac_f32_e32 v26, v242, v215
	v_fmac_f32_e32 v25, v167, v216
	v_fmac_f32_e32 v26, v243, v216
	v_add_u32_e32 v27, s100, v27
	v_add_u32_e32 v28, s100, v28
	ds_read_b128 v[172:175], v27
	ds_read_b128 v[176:179], v27 offset:16
	ds_read_b128 v[180:183], v27 offset:32
	ds_read_b128 v[164:167], v27 offset:48
	ds_read_b128 v[228:231], v28
	ds_read_b128 v[232:235], v28 offset:16
	ds_read_b128 v[236:239], v28 offset:32
	ds_read_b128 v[240:243], v28 offset:48
	v_mul_f32_e64 v17, |v25|, s61
	v_mul_f32_e64 v18, |v26|, s61
	v_exp_f32_e32 v17, v17
	v_exp_f32_e32 v18, v18
	v_min_f32_e32 v19, 0, v25
	v_min_f32_e32 v20, 0, v26
	v_add_f32_e32 v17, 1.0, v17
	v_add_f32_e32 v18, 1.0, v18
	v_cmp_gt_f32_e64 s[4:5], s24, v17
	v_cmp_gt_f32_e64 s[6:7], s24, v18
	s_nop 1
	v_cndmask_b32_e64 v21, 0, 32, s[4:5]
	v_cndmask_b32_e64 v22, 0, 32, s[6:7]
	v_ldexp_f32 v17, v17, v21
	v_ldexp_f32 v18, v18, v22
	v_log_f32_e32 v17, v17
	v_log_f32_e32 v18, v18
	v_cndmask_b32_e64 v21, 0, v192, s[4:5]
	v_cndmask_b32_e64 v22, 0, v192, s[6:7]
	v_mul_f32_e32 v23, 0x3f317217, v17
	v_mul_f32_e32 v24, 0x3f317217, v18
	v_fma_f32 v23, v17, s62, -v23
	v_fma_f32 v24, v18, s62, -v24
	v_fmac_f32_e32 v23, 0x3377d1cf, v17
	v_fmac_f32_e32 v24, 0x3377d1cf, v18
	v_fmac_f32_e32 v23, 0x3f317217, v17
	v_fmac_f32_e32 v24, 0x3f317217, v18
	v_cmp_lt_f32_e64 s[30:31], |v17|, s63
	v_cmp_lt_f32_e64 s[36:37], |v18|, s63
	s_nop 1
	v_cndmask_b32_e64 v17, v17, v23, s[30:31]
	v_cndmask_b32_e64 v18, v18, v24, s[36:37]
	v_sub_f32_e32 v17, v17, v21
	v_sub_f32_e32 v18, v18, v22
	v_sub_f32_e32 v17, v19, v17
	v_sub_f32_e32 v18, v20, v18
	v_fma_f32 v185, v17, s2, v184
	v_fma_f32 v162, v18, s2, v185
	s_waitcnt lgkmcnt(0)
	v_mov_b32_e32 v25, v140
	v_mov_b32_e32 v26, v140
	v_fmac_f32_e32 v25, v172, v201
	v_fmac_f32_e32 v26, v228, v201
	v_fmac_f32_e32 v25, v173, v202
	v_fmac_f32_e32 v26, v229, v202
	v_fmac_f32_e32 v25, v174, v203
	v_fmac_f32_e32 v26, v230, v203
	v_fmac_f32_e32 v25, v175, v204
	v_fmac_f32_e32 v26, v231, v204
	v_fmac_f32_e32 v25, v176, v205
	v_fmac_f32_e32 v26, v232, v205
	v_fmac_f32_e32 v25, v177, v206
	v_fmac_f32_e32 v26, v233, v206
	v_fmac_f32_e32 v25, v178, v207
	v_fmac_f32_e32 v26, v234, v207
	v_fmac_f32_e32 v25, v179, v208
	v_fmac_f32_e32 v26, v235, v208
	v_fmac_f32_e32 v25, v180, v209
	v_fmac_f32_e32 v26, v236, v209
	v_fmac_f32_e32 v25, v181, v210
	v_fmac_f32_e32 v26, v237, v210
	v_fmac_f32_e32 v25, v182, v211
	v_fmac_f32_e32 v26, v238, v211
	v_fmac_f32_e32 v25, v183, v212
	v_fmac_f32_e32 v26, v239, v212
	v_fmac_f32_e32 v25, v164, v213
	v_fmac_f32_e32 v26, v240, v213
	v_fmac_f32_e32 v25, v165, v214
	v_fmac_f32_e32 v26, v241, v214
	v_fmac_f32_e32 v25, v166, v215
	v_fmac_f32_e32 v26, v242, v215
	v_fmac_f32_e32 v25, v167, v216
	v_fmac_f32_e32 v26, v243, v216
	v_mul_f32_e64 v17, |v25|, s61
	v_mul_f32_e64 v18, |v26|, s61
	v_exp_f32_e32 v17, v17
	v_exp_f32_e32 v18, v18
	v_min_f32_e32 v19, 0, v25
	v_min_f32_e32 v20, 0, v26
	v_add_f32_e32 v17, 1.0, v17
	v_add_f32_e32 v18, 1.0, v18
	v_cmp_gt_f32_e64 s[4:5], s24, v17
	v_cmp_gt_f32_e64 s[6:7], s24, v18
	s_nop 1
	v_cndmask_b32_e64 v21, 0, 32, s[4:5]
	v_cndmask_b32_e64 v22, 0, 32, s[6:7]
	v_ldexp_f32 v17, v17, v21
	v_ldexp_f32 v18, v18, v22
	v_log_f32_e32 v17, v17
	v_log_f32_e32 v18, v18
	v_cndmask_b32_e64 v21, 0, v192, s[4:5]
	v_cndmask_b32_e64 v22, 0, v192, s[6:7]
	v_mul_f32_e32 v23, 0x3f317217, v17
	v_mul_f32_e32 v24, 0x3f317217, v18
	v_fma_f32 v23, v17, s62, -v23
	v_fma_f32 v24, v18, s62, -v24
	v_fmac_f32_e32 v23, 0x3377d1cf, v17
	v_fmac_f32_e32 v24, 0x3377d1cf, v18
	v_fmac_f32_e32 v23, 0x3f317217, v17
	v_fmac_f32_e32 v24, 0x3f317217, v18
	v_cmp_lt_f32_e64 s[30:31], |v17|, s63
	v_cmp_lt_f32_e64 s[36:37], |v18|, s63
	s_nop 1
	v_cndmask_b32_e64 v17, v17, v23, s[30:31]
	v_cndmask_b32_e64 v18, v18, v24, s[36:37]
	v_sub_f32_e32 v17, v17, v21
	v_sub_f32_e32 v18, v18, v22
	v_sub_f32_e32 v17, v19, v17
	v_sub_f32_e32 v18, v20, v18
	v_fma_f32 v163, v17, s2, v162
	v_fma_f32 v168, v18, s2, v163
	ds_write_b32 v135, v168 offset:45824
	s_waitcnt lgkmcnt(0)
	s_barrier
; __device__ __forceinline__ void gla_b(const Args& a, int l, int hd, int dir, int t0, unsigned char* sm, const bf16_t* __restrict__ PLR) {
;     ...
;     tot[q * 128 + d] = run;
;     __syncthreads();
;     float off = 0.f;
;     for (int qq = 0; qq < q; ++qq) off += tot[qq * 128 + d];
;     if (q > 0) for (int k = 0; k < 16; ++k) { const int s = q * 16 + k, j = dir ? 63 - s : s; Gb[j * 129 + d] += off; }
;     __syncthreads();
	ds_read_b32 v17, v134 offset:45824
	ds_read_b32 v18, v134 offset:46336
	ds_read_b32 v19, v134 offset:46848
	v_lshrrev_b32_e32 v15, 7, v171
	v_cmp_lt_u32_e64 s[4:5], 0, v15
	v_cmp_lt_u32_e64 s[6:7], 1, v15
	v_cmp_lt_u32_e64 s[30:31], 2, v15
	s_waitcnt lgkmcnt(0)
	v_cndmask_b32_e64 v17, 0, v17, s[4:5]
	v_cndmask_b32_e64 v18, 0, v18, s[6:7]
	v_cndmask_b32_e64 v19, 0, v19, s[30:31]
	v_add_f32_e32 v17, v17, v18
	v_add_f32_e32 v17, v17, v19
	v_add_f32_e32 v21, v217, v17
	ds_write_b32 v16, v21
	v_add_u32_e32 v16, s101, v16
	v_add_f32_e32 v22, v218, v17
	ds_write_b32 v16, v22
	v_add_u32_e32 v16, s101, v16
	v_add_f32_e32 v21, v219, v17
	ds_write_b32 v16, v21
	v_add_u32_e32 v16, s101, v16
	v_add_f32_e32 v22, v220, v17
	ds_write_b32 v16, v22
	v_add_u32_e32 v16, s101, v16
	v_add_f32_e32 v21, v221, v17
	ds_write_b32 v16, v21
	v_add_u32_e32 v16, s101, v16
	v_add_f32_e32 v22, v222, v17
	ds_write_b32 v16, v22
	v_add_u32_e32 v16, s101, v16
	v_add_f32_e32 v21, v223, v17
	ds_write_b32 v16, v21
	v_add_u32_e32 v16, s101, v16
	v_add_f32_e32 v22, v224, v17
	ds_write_b32 v16, v22
	v_add_u32_e32 v16, s101, v16
	v_add_f32_e32 v21, v225, v17
	ds_write_b32 v16, v21
	v_add_u32_e32 v16, s101, v16
	v_add_f32_e32 v22, v226, v17
	ds_write_b32 v16, v22
	v_add_u32_e32 v16, s101, v16
	v_add_f32_e32 v21, v227, v17
	ds_write_b32 v16, v21
	v_add_u32_e32 v16, s101, v16
	v_add_f32_e32 v22, v184, v17
	ds_write_b32 v16, v22
	v_add_u32_e32 v16, s101, v16
	v_add_f32_e32 v21, v185, v17
	ds_write_b32 v16, v21
	v_add_u32_e32 v16, s101, v16
	v_add_f32_e32 v22, v162, v17
	ds_write_b32 v16, v22
	v_add_u32_e32 v16, s101, v16
	v_add_f32_e32 v21, v163, v17
	ds_write_b32 v16, v21
	v_add_u32_e32 v16, s101, v16
	v_add_f32_e32 v22, v168, v17
	ds_write_b32 v16, v22
	s_cmpk_lt_u32 s28, 0x400
	s_cselect_b64 s[0:1], -1, 0
	s_mov_b64 s[6:7], exec
	v_readlane_b32 s64, v248, 45
	v_readlane_b32 s65, v248, 46
	v_readlane_b32 s66, v248, 47
	v_readlane_b32 s67, v248, 48
	v_readlane_b32 s68, v248, 49
	v_readlane_b32 s69, v248, 50
	v_readlane_b32 s70, v248, 51
	v_readlane_b32 s71, v248, 52
	v_readlane_b32 s72, v248, 53
	v_readlane_b32 s73, v248, 54
	v_readlane_b32 s74, v248, 55
	v_readlane_b32 s75, v248, 56
	v_readlane_b32 s76, v248, 57
	v_readlane_b32 s77, v248, 58
	v_readlane_b32 s78, v248, 59
	v_readlane_b32 s79, v248, 60
